# prompt attention unit: K/V staging loop unrolled, all six loads issued before the first wait (vmcnt 4/2/0)
# speedup vs baseline: 1.0028x; 1.0028x over previous
.LBB0_535:
	s_and_b64 vcc, exec, s[14:15]
	s_cbranch_vccz .LBB0_515
	s_and_b32 s62, s24, 1
	s_lshl_b32 s14, s62, 8
	s_ashr_i32 s18, s24, 7
	s_bfe_u32 s41, s24, 0x60001
	s_add_i32 s14, s14, s55
	s_lshl_b32 s63, s18, 12
	s_lshl_b32 s61, s41, 6
	s_ashr_i32 s15, s14, 31
	s_or_b32 s40, s61, s63
	s_lshl_b64 s[14:15], s[14:15], 1
	s_add_u32 s14, s42, s14
	s_addc_u32 s15, s43, s15
	s_waitcnt vmcnt(0)
	v_or_b32_e32 v40, s40, v129
	v_mov_b64_e32 v[4:5], s[14:15]
	v_mad_i64_i32 v[38:39], s[14:15], v40, s95, v[4:5]
	v_lshlrev_b32_e32 v2, 1, v76
	v_lshl_add_u64 v[38:39], v[38:39], 0, v[2:3]
	global_load_dwordx4 v[50:53], v[38:39], off
	global_load_dwordx4 v[46:49], v[38:39], off offset:64
	v_or_b32_e32 v38, 16, v40
	v_mad_i64_i32 v[4:5], s[14:15], v38, s95, v[4:5]
	v_lshl_add_u64 v[4:5], v[4:5], 0, v[2:3]
	global_load_dwordx4 v[42:45], v[4:5], off
	global_load_dwordx4 v[38:41], v[4:5], off offset:64
	s_and_saveexec_b64 s[14:15], s[38:39]
	s_cbranch_execz .LBB0_543
	s_add_i32 s64, s61, 0xffffff80
	s_cmp_gt_u32 s41, 61
	s_cselect_b64 s[16:17], -1, 0
	s_add_i32 s18, s18, s30
	s_ashr_i32 s19, s18, 31
	s_lshl_b64 s[18:19], s[18:19], 7
	s_add_i32 s20, s61, 0xfffff080
	s_add_u32 s18, s18, s20
	s_addc_u32 s19, s19, 0
	s_or_b32 s20, s62, 0xffffff00
	s_ashr_i32 s21, s20, 31
	s_lshl_b64 s[20:21], s[20:21], 6
	s_lshl_b32 s22, s62, 7
	s_add_u32 s22, s56, s22
	s_addc_u32 s23, s57, 0
	s_mov_b64 s[24:25], 0
	v_ashrrev_i32_e32 v4, 3, v74
	v_add_u32_e32 v2, s64, v4
	v_max_i32_e32 v2, 0, v2
	v_add_u32_e32 v54, s63, v2
	v_ashrrev_i32_e32 v55, 31, v54
	v_lshlrev_b64 v[54:55], 9, v[54:55]
	v_and_b32_e32 v68, 56, v75
	v_lshl_add_u64 v[54:55], s[22:23], 0, v[54:55]
	v_lshlrev_b32_e32 v2, 1, v68
	v_lshl_add_u64 v[58:59], v[54:55], 0, v[2:3]
	global_load_dwordx4 v[170:173], v[58:59], off
	global_load_dwordx4 v[174:177], v[58:59], off offset:256
	v_add_u32_e32 v206, 0x200, v74
	v_add_u32_e32 v208, 0x1000, v75
	v_ashrrev_i32_e32 v4, 3, v206
	v_add_u32_e32 v2, s64, v4
	v_max_i32_e32 v2, 0, v2
	v_add_u32_e32 v54, s63, v2
	v_ashrrev_i32_e32 v55, 31, v54
	v_lshlrev_b64 v[54:55], 9, v[54:55]
	v_and_b32_e32 v68, 56, v208
	v_lshl_add_u64 v[54:55], s[22:23], 0, v[54:55]
	v_lshlrev_b32_e32 v2, 1, v68
	v_lshl_add_u64 v[58:59], v[54:55], 0, v[2:3]
	global_load_dwordx4 v[178:181], v[58:59], off
	global_load_dwordx4 v[182:185], v[58:59], off offset:256
	v_add_u32_e32 v207, 0x400, v74
	v_add_u32_e32 v209, 0x2000, v75
	v_ashrrev_i32_e32 v4, 3, v207
	v_add_u32_e32 v2, s64, v4
	v_max_i32_e32 v2, 0, v2
	v_add_u32_e32 v54, s63, v2
	v_ashrrev_i32_e32 v55, 31, v54
	v_lshlrev_b64 v[54:55], 9, v[54:55]
	v_and_b32_e32 v68, 56, v209
	v_lshl_add_u64 v[54:55], s[22:23], 0, v[54:55]
	v_lshlrev_b32_e32 v2, 1, v68
	v_lshl_add_u64 v[58:59], v[54:55], 0, v[2:3]
	global_load_dwordx4 v[186:189], v[58:59], off
	global_load_dwordx4 v[190:193], v[58:59], off offset:256
	v_ashrrev_i32_e32 v4, 3, v74
	v_add_u32_e32 v2, s64, v4
	v_cmp_lt_i32_e32 vcc, -1, v2
	v_and_b32_e32 v68, 56, v75
	v_lshlrev_b32_e32 v2, 1, v68
	v_mul_lo_u32 v5, v4, s94
	v_add3_u32 v2, 0, v5, v2
	s_waitcnt vmcnt(4)
	v_cndmask_b32_e32 v58, 0, v170, vcc
	v_cndmask_b32_e32 v59, 0, v171, vcc
	v_cndmask_b32_e32 v60, 0, v172, vcc
	v_cndmask_b32_e32 v61, 0, v173, vcc
	v_cndmask_b32_e32 v54, 0, v174, vcc
	v_cndmask_b32_e32 v55, 0, v175, vcc
	v_cndmask_b32_e32 v56, 0, v176, vcc
	v_cndmask_b32_e32 v57, 0, v177, vcc
	v_cmp_lt_i32_e32 vcc, s8, v4
	ds_write_b128 v2, v[58:61]
	v_lshl_add_u32 v2, v4, 4, v2
	s_and_b64 s[26:27], s[16:17], vcc
	v_mov_b64_e32 v[62:63], 0
	v_mov_b64_e32 v[64:65], 0
	ds_write_b128 v2, v[54:57] offset:27648
	s_and_saveexec_b64 s[28:29], s[26:27]
	v_mov_b32_e32 v5, v3
	v_lshl_add_u64 v[4:5], s[18:19], 0, v[4:5]
	v_lshlrev_b64 v[4:5], 7, v[4:5]
	v_lshl_add_u64 v[4:5], v[4:5], 0, s[20:21]
	v_or_b32_e32 v4, v4, v68
	v_lshlrev_b64 v[4:5], 2, v[4:5]
	v_lshl_add_u64 v[64:65], s[50:51], 0, v[4:5]
	v_lshl_add_u64 v[62:63], s[52:53], 0, v[4:5]
	s_or_b64 exec, exec, s[28:29]
	v_cmp_ne_u64_e32 vcc, 0, v[64:65]
	s_and_saveexec_b64 s[26:27], vcc
	s_cbranch_execz .Lat_sk0
	v_lshlrev_b32_e32 v68, 16, v58
	v_and_b32_e32 v69, 0xffff0000, v58
	v_lshlrev_b32_e32 v70, 16, v59
	v_and_b32_e32 v71, 0xffff0000, v59
	v_lshlrev_b32_e32 v58, 16, v60
	v_and_b32_e32 v59, 0xffff0000, v60
	v_lshlrev_b32_e32 v60, 16, v61
	v_and_b32_e32 v61, 0xffff0000, v61
	v_lshlrev_b32_e32 v90, 16, v54
	v_and_b32_e32 v91, 0xffff0000, v54
	v_lshlrev_b32_e32 v92, 16, v55
	v_and_b32_e32 v93, 0xffff0000, v55
	v_lshlrev_b32_e32 v54, 16, v56
	v_and_b32_e32 v55, 0xffff0000, v56
	v_lshlrev_b32_e32 v56, 16, v57
	v_and_b32_e32 v57, 0xffff0000, v57
	global_store_dwordx4 v[64:65], v[68:71], off
	global_store_dwordx4 v[64:65], v[58:61], off offset:16
	global_store_dwordx4 v[62:63], v[90:93], off
	global_store_dwordx4 v[62:63], v[54:57], off offset:16
.Lat_sk0:
	s_or_b64 exec, exec, s[26:27]
	v_ashrrev_i32_e32 v4, 3, v206
	v_add_u32_e32 v2, s64, v4
	v_cmp_lt_i32_e32 vcc, -1, v2
	v_and_b32_e32 v68, 56, v208
	v_lshlrev_b32_e32 v2, 1, v68
	v_mul_lo_u32 v5, v4, s94
	v_add3_u32 v2, 0, v5, v2
	s_waitcnt vmcnt(2)
	v_cndmask_b32_e32 v58, 0, v178, vcc
	v_cndmask_b32_e32 v59, 0, v179, vcc
	v_cndmask_b32_e32 v60, 0, v180, vcc
	v_cndmask_b32_e32 v61, 0, v181, vcc
	v_cndmask_b32_e32 v54, 0, v182, vcc
	v_cndmask_b32_e32 v55, 0, v183, vcc
	v_cndmask_b32_e32 v56, 0, v184, vcc
	v_cndmask_b32_e32 v57, 0, v185, vcc
	v_cmp_lt_i32_e32 vcc, s8, v4
	ds_write_b128 v2, v[58:61]
	v_lshl_add_u32 v2, v4, 4, v2
	s_and_b64 s[26:27], s[16:17], vcc
	v_mov_b64_e32 v[62:63], 0
	v_mov_b64_e32 v[64:65], 0
	ds_write_b128 v2, v[54:57] offset:27648
	s_and_saveexec_b64 s[28:29], s[26:27]
	v_mov_b32_e32 v5, v3
	v_lshl_add_u64 v[4:5], s[18:19], 0, v[4:5]
	v_lshlrev_b64 v[4:5], 7, v[4:5]
	v_lshl_add_u64 v[4:5], v[4:5], 0, s[20:21]
	v_or_b32_e32 v4, v4, v68
	v_lshlrev_b64 v[4:5], 2, v[4:5]
	v_lshl_add_u64 v[64:65], s[50:51], 0, v[4:5]
	v_lshl_add_u64 v[62:63], s[52:53], 0, v[4:5]
	s_or_b64 exec, exec, s[28:29]
	v_cmp_ne_u64_e32 vcc, 0, v[64:65]
	s_and_saveexec_b64 s[26:27], vcc
	s_cbranch_execz .Lat_sk1
	v_lshlrev_b32_e32 v68, 16, v58
	v_and_b32_e32 v69, 0xffff0000, v58
	v_lshlrev_b32_e32 v70, 16, v59
	v_and_b32_e32 v71, 0xffff0000, v59
	v_lshlrev_b32_e32 v58, 16, v60
	v_and_b32_e32 v59, 0xffff0000, v60
	v_lshlrev_b32_e32 v60, 16, v61
	v_and_b32_e32 v61, 0xffff0000, v61
	v_lshlrev_b32_e32 v90, 16, v54
	v_and_b32_e32 v91, 0xffff0000, v54
	v_lshlrev_b32_e32 v92, 16, v55
	v_and_b32_e32 v93, 0xffff0000, v55
	v_lshlrev_b32_e32 v54, 16, v56
	v_and_b32_e32 v55, 0xffff0000, v56
	v_lshlrev_b32_e32 v56, 16, v57
	v_and_b32_e32 v57, 0xffff0000, v57
	global_store_dwordx4 v[64:65], v[68:71], off
	global_store_dwordx4 v[64:65], v[58:61], off offset:16
	global_store_dwordx4 v[62:63], v[90:93], off
	global_store_dwordx4 v[62:63], v[54:57], off offset:16
.Lat_sk1:
	s_or_b64 exec, exec, s[26:27]
	v_ashrrev_i32_e32 v4, 3, v207
	v_add_u32_e32 v2, s64, v4
	v_cmp_lt_i32_e32 vcc, -1, v2
	v_and_b32_e32 v68, 56, v209
	v_lshlrev_b32_e32 v2, 1, v68
	v_mul_lo_u32 v5, v4, s94
	v_add3_u32 v2, 0, v5, v2
	s_waitcnt vmcnt(0)
	v_cndmask_b32_e32 v58, 0, v186, vcc
	v_cndmask_b32_e32 v59, 0, v187, vcc
	v_cndmask_b32_e32 v60, 0, v188, vcc
	v_cndmask_b32_e32 v61, 0, v189, vcc
	v_cndmask_b32_e32 v54, 0, v190, vcc
	v_cndmask_b32_e32 v55, 0, v191, vcc
	v_cndmask_b32_e32 v56, 0, v192, vcc
	v_cndmask_b32_e32 v57, 0, v193, vcc
	v_cmp_lt_i32_e32 vcc, s8, v4
	ds_write_b128 v2, v[58:61]
	v_lshl_add_u32 v2, v4, 4, v2
	s_and_b64 s[26:27], s[16:17], vcc
	v_mov_b64_e32 v[62:63], 0
	v_mov_b64_e32 v[64:65], 0
	ds_write_b128 v2, v[54:57] offset:27648
	s_and_saveexec_b64 s[28:29], s[26:27]
	v_mov_b32_e32 v5, v3
	v_lshl_add_u64 v[4:5], s[18:19], 0, v[4:5]
	v_lshlrev_b64 v[4:5], 7, v[4:5]
	v_lshl_add_u64 v[4:5], v[4:5], 0, s[20:21]
	v_or_b32_e32 v4, v4, v68
	v_lshlrev_b64 v[4:5], 2, v[4:5]
	v_lshl_add_u64 v[64:65], s[50:51], 0, v[4:5]
	v_lshl_add_u64 v[62:63], s[52:53], 0, v[4:5]
	s_or_b64 exec, exec, s[28:29]
	v_cmp_ne_u64_e32 vcc, 0, v[64:65]
	s_and_saveexec_b64 s[26:27], vcc
	s_cbranch_execz .Lat_sk2
	v_lshlrev_b32_e32 v68, 16, v58
	v_and_b32_e32 v69, 0xffff0000, v58
	v_lshlrev_b32_e32 v70, 16, v59
	v_and_b32_e32 v71, 0xffff0000, v59
	v_lshlrev_b32_e32 v58, 16, v60
	v_and_b32_e32 v59, 0xffff0000, v60
	v_lshlrev_b32_e32 v60, 16, v61
	v_and_b32_e32 v61, 0xffff0000, v61
	v_lshlrev_b32_e32 v90, 16, v54
	v_and_b32_e32 v91, 0xffff0000, v54
	v_lshlrev_b32_e32 v92, 16, v55
	v_and_b32_e32 v93, 0xffff0000, v55
	v_lshlrev_b32_e32 v54, 16, v56
	v_and_b32_e32 v55, 0xffff0000, v56
	v_lshlrev_b32_e32 v56, 16, v57
	v_and_b32_e32 v57, 0xffff0000, v57
	global_store_dwordx4 v[64:65], v[68:71], off
	global_store_dwordx4 v[64:65], v[58:61], off offset:16
	global_store_dwordx4 v[62:63], v[90:93], off
	global_store_dwordx4 v[62:63], v[54:57], off offset:16
.Lat_sk2:
	s_or_b64 exec, exec, s[26:27]
.LBB0_543:
	s_or_b64 exec, exec, s[14:15]
	s_waitcnt lgkmcnt(0)
	s_barrier
	ds_read_b128 v[54:57], v122
	ds_read_b128 v[58:61], v122 offset:64
	s_lshl_b32 s14, s62, 12
	s_waitcnt vmcnt(3) lgkmcnt(1)
	v_mfma_f32_16x16x32_bf16 v[54:57], v[54:57], v[50:53], 0
	ds_read_b128 v[62:65], v122 offset:2304
	ds_read_b128 v[66:69], v122 offset:2368
	s_add_i32 s19, s14, 0
	s_lshl_b32 s20, s62, 2
	s_waitcnt vmcnt(2) lgkmcnt(2)
	v_mfma_f32_16x16x32_bf16 v[54:57], v[58:61], v[46:49], v[54:57]
	ds_read_b128 v[58:61], v122 offset:4608
	ds_read_b128 v[70:73], v122 offset:4672
	s_load_dwordx2 s[14:15], s[12:13], 0x78
	s_add_i32 s16, s58, s20
	s_ashr_i32 s17, s16, 31
	s_lshl_b64 s[16:17], s[16:17], 2
	ds_read_b128 v[90:93], v122 offset:6912
	ds_read_b128 v[94:97], v122 offset:6976
	s_waitcnt lgkmcnt(0)
	s_add_u32 s14, s14, s16
	s_addc_u32 s15, s15, s17
	global_load_dword v108, v3, s[14:15]
	v_mfma_f32_16x16x32_bf16 v[62:65], v[62:65], v[50:53], 0
	ds_read_b128 v[98:101], v122 offset:9280
	ds_read_b128 v[102:105], v122 offset:11584
	v_lshl_add_u32 v2, v130, 2, s19
	v_mfma_f32_16x16x32_bf16 v[58:61], v[58:61], v[50:53], 0
	v_add_u32_e32 v4, 0x1ad00, v2
	v_add_u32_e32 v107, 0x1adc8, v2
	v_add_u32_e32 v89, 0x1ad88, v2
	v_mfma_f32_16x16x32_bf16 v[90:93], v[90:93], v[50:53], 0
	v_add_u32_e32 v106, 0x1adc0, v2
	v_add_u32_e32 v109, 0x1ae00, v2
	v_add_u32_e32 v164, 0x1ae48, v2
	v_mfma_f32_16x16x32_bf16 v[64:67], v[66:69], v[46:49], v[62:65]
	v_add_u32_e32 v162, 0x1ae08, v2
	v_add_u32_e32 v163, 0x1ae40, v2
	v_add_u32_e32 v165, 0x1ae80, v2
	v_mfma_f32_16x16x32_bf16 v[58:61], v[70:73], v[46:49], v[58:61]
	ds_read_b128 v[68:71], v122 offset:9216
	v_add_u32_e32 v72, 0x1ad48, v2
	v_add_u32_e32 v62, 0x1ad08, v2
	v_mfma_f32_16x16x32_bf16 v[90:93], v[94:97], v[46:49], v[90:93]
	ds_read_b128 v[94:97], v122 offset:11520
	ds_read_b128 v[110:113], v122 offset:13888
	s_waitcnt lgkmcnt(2)
	v_mfma_f32_16x16x32_bf16 v[68:71], v[68:71], v[50:53], 0
	v_add_u32_e32 v63, 0x1ad40, v2
	v_add_u32_e32 v73, 0x1ad80, v2
	v_add_u32_e32 v168, 0x1aec8, v2
	s_waitcnt lgkmcnt(1)
	v_mfma_f32_16x16x32_bf16 v[94:97], v[94:97], v[50:53], 0
	v_add_u32_e32 v166, 0x1ae88, v2
	v_add_u32_e32 v167, 0x1aec0, v2
	v_add_u32_e32 v169, 0x1af00, v2
	v_mfma_f32_16x16x32_bf16 v[98:101], v[98:101], v[46:49], v[68:71]
	s_sub_i32 s14, 0x80, s61
	s_cmp_lt_u32 s41, 2
	s_cselect_b32 s18, s14, 0
	ds_read_b128 v[68:71], v122 offset:13824
	v_mfma_f32_16x16x32_bf16 v[102:105], v[102:105], v[46:49], v[94:97]
	s_nop 2
	ds_read_b128 v[94:97], v122 offset:16128
	ds_read_b128 v[114:117], v122 offset:16192
	ds_read_b128 v[134:137], v122 offset:18432
	ds_read_b128 v[138:141], v122 offset:18496
	ds_read_b128 v[142:145], v122 offset:20736
	ds_read_b128 v[146:149], v122 offset:20800
	ds_read_b128 v[150:153], v122 offset:23040
	ds_read_b128 v[154:157], v122 offset:23104
	s_cmp_lg_u32 s18, 0
	s_waitcnt lgkmcnt(7)
	v_mfma_f32_16x16x32_bf16 v[94:97], v[94:97], v[50:53], 0
	s_cselect_b64 s[14:15], -1, 0
	s_and_b64 vcc, exec, s[14:15]
	v_mfma_f32_16x16x32_bf16 v[68:71], v[68:71], v[50:53], 0
	s_waitcnt lgkmcnt(6)
	v_mfma_f32_16x16x32_bf16 v[114:117], v[114:117], v[46:49], v[94:97]
	s_waitcnt lgkmcnt(5)
	v_mfma_f32_16x16x32_bf16 v[94:97], v[134:137], v[50:53], 0
	v_mfma_f32_16x16x32_bf16 v[110:113], v[110:113], v[46:49], v[68:71]
	s_nop 2
	ds_read_b128 v[68:71], v122 offset:25344
	ds_read_b128 v[158:161], v122 offset:25408
	s_waitcnt lgkmcnt(6)
	v_mfma_f32_16x16x32_bf16 v[134:137], v[138:141], v[46:49], v[94:97]
	s_waitcnt lgkmcnt(5)
	v_mfma_f32_16x16x32_bf16 v[94:97], v[142:145], v[50:53], 0
	s_waitcnt lgkmcnt(4)
	v_mfma_f32_16x16x32_bf16 v[138:141], v[146:149], v[46:49], v[94:97]
	s_waitcnt lgkmcnt(3)
	v_mfma_f32_16x16x32_bf16 v[94:97], v[150:153], v[50:53], 0
	v_add_u32_e32 v152, 0x1af48, v2
	v_add_u32_e32 v150, 0x1af08, v2
	v_add_u32_e32 v151, 0x1af40, v2
	s_waitcnt lgkmcnt(1)
	v_mfma_f32_16x16x32_bf16 v[50:53], v[68:71], v[50:53], 0
	ds_read2_b32 v[4:5], v4 offset1:1
	ds_read2_b32 v[68:69], v62 offset1:1
	ds_read2_b32 v[70:71], v63 offset1:1
	v_add_u32_e32 v153, 0x1af80, v2
	s_waitcnt lgkmcnt(2)
	v_pk_fma_f32 v[62:63], v[54:55], s[10:11], v[4:5] op_sel_hi:[1,0,1]
	v_mfma_f32_16x16x32_bf16 v[142:145], v[154:157], v[46:49], v[94:97]
	s_waitcnt lgkmcnt(1)
	v_pk_fma_f32 v[4:5], v[56:57], s[10:11], v[68:69] op_sel_hi:[1,0,1]
	s_waitcnt lgkmcnt(0)
	v_pk_fma_f32 v[64:65], v[64:65], s[10:11], v[70:71] op_sel_hi:[1,0,1]
	v_add_u32_e32 v154, 0x1af88, v2
	v_mfma_f32_16x16x32_bf16 v[146:149], v[158:161], v[46:49], v[50:53]
	ds_read2_b32 v[46:47], v72 offset1:1
	ds_read2_b32 v[48:49], v73 offset1:1
	s_nop 0
	ds_read2_b32 v[50:51], v89 offset1:1
	ds_read2_b32 v[52:53], v106 offset1:1
	v_add_u32_e32 v155, 0x1afc0, v2
	v_add_u32_e32 v2, 0x1afc8, v2
	s_waitcnt lgkmcnt(2)
	v_pk_fma_f32 v[70:71], v[58:59], s[10:11], v[48:49] op_sel_hi:[1,0,1]
	v_pk_fma_f32 v[66:67], v[66:67], s[10:11], v[46:47] op_sel_hi:[1,0,1]
	ds_read2_b32 v[46:47], v107 offset1:1
	s_waitcnt lgkmcnt(2)
	v_pk_fma_f32 v[68:69], v[60:61], s[10:11], v[50:51] op_sel_hi:[1,0,1]
	s_waitcnt lgkmcnt(1)
	v_pk_fma_f32 v[72:73], v[90:91], s[10:11], v[52:53] op_sel_hi:[1,0,1]
	ds_read2_b32 v[48:49], v109 offset1:1
	ds_read2_b32 v[50:51], v162 offset1:1
	ds_read2_b32 v[52:53], v163 offset1:1
	s_waitcnt lgkmcnt(3)
	v_pk_fma_f32 v[90:91], v[92:93], s[10:11], v[46:47] op_sel_hi:[1,0,1]
	ds_read2_b32 v[46:47], v164 offset1:1
	s_waitcnt lgkmcnt(3)
	v_pk_fma_f32 v[94:95], v[98:99], s[10:11], v[48:49] op_sel_hi:[1,0,1]
	s_waitcnt lgkmcnt(2)
	v_pk_fma_f32 v[92:93], v[100:101], s[10:11], v[50:51] op_sel_hi:[1,0,1]
	s_waitcnt lgkmcnt(1)
	v_pk_fma_f32 v[96:97], v[102:103], s[10:11], v[52:53] op_sel_hi:[1,0,1]
	ds_read2_b32 v[48:49], v165 offset1:1
	ds_read2_b32 v[50:51], v166 offset1:1
	ds_read2_b32 v[52:53], v167 offset1:1
	s_waitcnt lgkmcnt(3)
	v_pk_fma_f32 v[98:99], v[104:105], s[10:11], v[46:47] op_sel_hi:[1,0,1]
	ds_read2_b32 v[46:47], v168 offset1:1
	s_waitcnt lgkmcnt(3)
	v_pk_fma_f32 v[102:103], v[110:111], s[10:11], v[48:49] op_sel_hi:[1,0,1]
	s_waitcnt lgkmcnt(2)
	v_pk_fma_f32 v[100:101], v[112:113], s[10:11], v[50:51] op_sel_hi:[1,0,1]
	s_waitcnt lgkmcnt(1)
	v_pk_fma_f32 v[104:105], v[114:115], s[10:11], v[52:53] op_sel_hi:[1,0,1]
	ds_read2_b32 v[48:49], v169 offset1:1
	ds_read2_b32 v[50:51], v150 offset1:1
	ds_read2_b32 v[52:53], v151 offset1:1
	s_waitcnt lgkmcnt(3)
	v_pk_fma_f32 v[106:107], v[116:117], s[10:11], v[46:47] op_sel_hi:[1,0,1]
	ds_read2_b32 v[46:47], v152 offset1:1
	s_waitcnt lgkmcnt(3)
	v_pk_fma_f32 v[60:61], v[134:135], s[10:11], v[48:49] op_sel_hi:[1,0,1]
	s_waitcnt lgkmcnt(2)
	v_pk_fma_f32 v[58:59], v[136:137], s[10:11], v[50:51] op_sel_hi:[1,0,1]
	ds_read2_b32 v[48:49], v153 offset1:1
	ds_read2_b32 v[50:51], v154 offset1:1
	ds_read2_b32 v[110:111], v155 offset1:1
	s_waitcnt lgkmcnt(4)
	v_pk_fma_f32 v[56:57], v[138:139], s[10:11], v[52:53] op_sel_hi:[1,0,1]
	s_waitcnt lgkmcnt(3)
	v_pk_fma_f32 v[54:55], v[140:141], s[10:11], v[46:47] op_sel_hi:[1,0,1]
	ds_read2_b32 v[46:47], v2 offset1:1
	s_waitcnt lgkmcnt(3)
	v_pk_fma_f32 v[52:53], v[142:143], s[10:11], v[48:49] op_sel_hi:[1,0,1]
	s_waitcnt lgkmcnt(2)
	v_pk_fma_f32 v[50:51], v[144:145], s[10:11], v[50:51] op_sel_hi:[1,0,1]
	s_waitcnt lgkmcnt(1)
	v_pk_fma_f32 v[48:49], v[146:147], s[10:11], v[110:111] op_sel_hi:[1,0,1]
	s_waitcnt lgkmcnt(0)
	v_pk_fma_f32 v[46:47], v[148:149], s[10:11], v[46:47] op_sel_hi:[1,0,1]
	s_cbranch_vccz .LBB0_548
	v_cmp_le_u32_e32 vcc, s18, v6
	s_nop 1
	v_cndmask_b32_e32 v156, v233, v62, vcc
	v_cmp_le_u32_e32 vcc, s18, v1
	s_nop 1
	v_cndmask_b32_e32 v155, v233, v63, vcc
	v_cmp_le_u32_e32 vcc, s18, v8
	s_nop 1
	v_cndmask_b32_e32 v154, v233, v4, vcc
	v_cmp_le_u32_e32 vcc, s18, v7
	s_nop 1
	v_cndmask_b32_e32 v153, v233, v5, vcc
	v_cmp_le_u32_e32 vcc, s18, v10
	s_nop 1
	v_cndmask_b32_e32 v152, v233, v64, vcc
	v_cmp_le_u32_e32 vcc, s18, v9
	s_nop 1
	v_cndmask_b32_e32 v151, v233, v65, vcc
	v_cmp_le_u32_e32 vcc, s18, v12
	s_nop 1
	v_cndmask_b32_e32 v150, v233, v66, vcc
	v_cmp_le_u32_e32 vcc, s18, v11
	s_nop 1
	v_cndmask_b32_e32 v149, v233, v67, vcc
	v_cmp_le_u32_e32 vcc, s18, v14
	s_nop 1
	v_cndmask_b32_e32 v148, v233, v70, vcc
	v_cmp_le_u32_e32 vcc, s18, v13
	s_nop 1
	v_cndmask_b32_e32 v147, v233, v71, vcc
	v_cmp_le_u32_e32 vcc, s18, v16
	s_nop 1
	v_cndmask_b32_e32 v146, v233, v68, vcc
	v_cmp_le_u32_e32 vcc, s18, v15
	s_nop 1
	v_cndmask_b32_e32 v145, v233, v69, vcc
	v_cmp_le_u32_e32 vcc, s18, v18
	s_nop 1
	v_cndmask_b32_e32 v144, v233, v72, vcc
	v_cmp_le_u32_e32 vcc, s18, v17
	s_nop 1
	v_cndmask_b32_e32 v143, v233, v73, vcc
	v_cmp_le_u32_e32 vcc, s18, v20
	s_nop 1
	v_cndmask_b32_e32 v142, v233, v90, vcc
	v_cmp_le_u32_e32 vcc, s18, v19
	s_nop 1
	v_cndmask_b32_e32 v141, v233, v91, vcc
	v_cmp_le_u32_e32 vcc, s18, v22
	s_nop 1
	v_cndmask_b32_e32 v140, v233, v94, vcc
	v_cmp_le_u32_e32 vcc, s18, v21
	s_nop 1
	v_cndmask_b32_e32 v139, v233, v95, vcc
	v_cmp_le_u32_e32 vcc, s18, v24
	s_nop 1
	v_cndmask_b32_e32 v138, v233, v92, vcc
	v_cmp_le_u32_e32 vcc, s18, v23
	s_nop 1
	v_cndmask_b32_e32 v137, v233, v93, vcc
	v_cmp_le_u32_e32 vcc, s18, v26
	s_nop 1
	v_cndmask_b32_e32 v136, v233, v96, vcc
	v_cmp_le_u32_e32 vcc, s18, v25
	s_nop 1
	v_cndmask_b32_e32 v135, v233, v97, vcc
	v_cmp_le_u32_e32 vcc, s18, v28
	s_nop 1
	v_cndmask_b32_e32 v134, v233, v98, vcc
	v_cmp_le_u32_e32 vcc, s18, v27
	s_nop 1
	v_cndmask_b32_e32 v117, v233, v99, vcc
	v_cmp_le_u32_e32 vcc, s18, v30
	s_nop 1
	v_cndmask_b32_e32 v116, v233, v102, vcc
	v_cmp_le_u32_e32 vcc, s18, v29
	s_nop 1
	v_cndmask_b32_e32 v115, v233, v103, vcc
	v_cmp_le_u32_e32 vcc, s18, v32
	s_nop 1
	v_cndmask_b32_e32 v114, v233, v100, vcc
	v_cmp_le_u32_e32 vcc, s18, v31
	s_nop 1
	v_cndmask_b32_e32 v113, v233, v101, vcc
	v_cmp_le_u32_e32 vcc, s18, v34
	s_nop 1
	v_cndmask_b32_e32 v112, v233, v104, vcc
	v_cmp_le_u32_e32 vcc, s18, v33
	s_nop 1
	v_cndmask_b32_e32 v111, v233, v105, vcc
	v_cmp_le_u32_e32 vcc, s18, v36
	s_nop 1
	v_cndmask_b32_e32 v110, v233, v106, vcc
	v_cmp_le_u32_e32 vcc, s18, v35
	s_nop 1
	v_cndmask_b32_e32 v109, v233, v107, vcc
	s_cbranch_execnz .LBB0_546
